# merge epilogue: PROJ LDS-DMA ring deepened from 3 to 5 chunks using the free As[1][1] staging slot (4 chunks prefetched ahead)
# speedup vs baseline: 1.0120x; 1.0091x over previous
.Lw2_nowait:
	v_lshl_add_u32 v250, s52, 8, v146
	v_lshl_or_b32 v251, s26, 6, v148
	v_lshlrev_b32_e32 v251, 1, v251
	v_mbcnt_lo_u32_b32 v140, -1, 0
	v_mbcnt_hi_u32_b32 v140, -1, v140
	v_lshrrev_b32_e32 v141, 3, v140
	s_lshl_b32 s27, s3, 3
	v_add_u32_e32 v141, s27, v141
	v_and_b32_e32 v142, 7, v140
	v_bfe_u32 v143, v141, 1, 3
	v_xor_b32_e32 v142, v142, v143
	v_and_b32_e32 v143, 31, v141
	v_lshrrev_b32_e32 v141, 5, v141
	v_lshrrev_b32_e32 v144, 4, v143
	v_and_b32_e32 v143, 15, v143
	v_lshl_or_b32 v143, v144, 6, v143
	s_lshl_b32 s27, s52, 8
	v_add_u32_e32 v143, s27, v143
	v_lshlrev_b32_e32 v143, 13, v143
	v_lshl_add_u32 v143, v141, 11, v143
	v_lshl_add_u32 v143, v142, 4, v143
	s_lshl_b32 s27, s26, 7
	v_add_u32_e32 v143, s27, v143
	s_lshl_b32 s27, s3, 10
	v_add_u32_e32 v253, 0x0, v143
	s_add_i32 m0, s27, 0x20000
	s_nop 0
	global_load_lds_dwordx4 v253, s[6:7]
	v_add_u32_e32 v253, 0x1000, v143
	s_add_i32 m0, s27, 0x22000
	s_nop 0
	global_load_lds_dwordx4 v253, s[6:7]
	v_add_u32_e32 v253, 0x20000, v143
	s_add_i32 m0, s27, 0x24000
	s_nop 0
	global_load_lds_dwordx4 v253, s[6:7]
	v_add_u32_e32 v253, 0x21000, v143
	s_add_i32 m0, s27, 0xc000
	s_nop 0
	global_load_lds_dwordx4 v253, s[6:7]
	v_lshrrev_b32_e32 v144, 6, v146
	v_and_b32_e32 v145, 15, v146
	v_lshl_or_b32 v144, v144, 4, v145
	v_bfe_u32 v145, v144, 1, 3
	v_lshrrev_b32_e32 v252, 4, v148
	v_bfe_u32 v254, v148, 3, 1
	v_lshl_or_b32 v252, v252, 1, v254
	v_xor_b32_e32 v252, v252, v145
	v_lshlrev_b32_e32 v252, 4, v252
	v_bfe_u32 v254, v148, 2, 1
	v_lshl_or_b32 v252, v254, 3, v252
	v_lshl_add_u32 v252, v144, 7, v252
	v_add_u32_e32 v198, 0xc000, v252
	v_add_u32_e32 v252, 0x20000, v252
	v_mov_b32_e32 v224, 0xbfb8aa3b
	v_mov_b32_e32 v225, 0xbfb8aa3b
	v_mov_b32_e32 v226, 1.0
	v_mov_b32_e32 v227, 1.0
	v_mov_b32_e32 v228, 0
	v_mov_b32_e32 v229, 0
	v_pk_mul_f32 v[150:151], v[126:127], v[224:225]
	v_pk_mul_f32 v[152:153], v[128:129], v[224:225]
	v_pk_mul_f32 v[154:155], v[122:123], v[224:225]
	v_pk_mul_f32 v[156:157], v[124:125], v[224:225]
	v_pk_mul_f32 v[158:159], v[118:119], v[224:225]
	v_pk_mul_f32 v[160:161], v[120:121], v[224:225]
	v_pk_mul_f32 v[162:163], v[114:115], v[224:225]
	v_pk_mul_f32 v[164:165], v[116:117], v[224:225]
	v_exp_f32_e32 v150, v150
	v_exp_f32_e32 v151, v151
	v_exp_f32_e32 v152, v152
	v_exp_f32_e32 v153, v153
	v_exp_f32_e32 v154, v154
	v_exp_f32_e32 v155, v155
	v_exp_f32_e32 v156, v156
	v_exp_f32_e32 v157, v157
	v_exp_f32_e32 v158, v158
	v_exp_f32_e32 v159, v159
	v_exp_f32_e32 v160, v160
	v_exp_f32_e32 v161, v161
	v_exp_f32_e32 v162, v162
	v_exp_f32_e32 v163, v163
	v_exp_f32_e32 v164, v164
	v_exp_f32_e32 v165, v165
	v_pk_add_f32 v[150:151], v[150:151], v[226:227]
	v_pk_add_f32 v[152:153], v[152:153], v[226:227]
	v_pk_add_f32 v[154:155], v[154:155], v[226:227]
	v_pk_add_f32 v[156:157], v[156:157], v[226:227]
	v_pk_add_f32 v[158:159], v[158:159], v[226:227]
	v_pk_add_f32 v[160:161], v[160:161], v[226:227]
	v_pk_add_f32 v[162:163], v[162:163], v[226:227]
	v_pk_add_f32 v[164:165], v[164:165], v[226:227]
	v_rcp_f32_e32 v150, v150
	v_rcp_f32_e32 v151, v151
	v_rcp_f32_e32 v152, v152
	v_rcp_f32_e32 v153, v153
	v_rcp_f32_e32 v154, v154
	v_rcp_f32_e32 v155, v155
	v_rcp_f32_e32 v156, v156
	v_rcp_f32_e32 v157, v157
	v_rcp_f32_e32 v158, v158
	v_rcp_f32_e32 v159, v159
	v_rcp_f32_e32 v160, v160
	v_rcp_f32_e32 v161, v161
	v_rcp_f32_e32 v162, v162
	v_rcp_f32_e32 v163, v163
	v_rcp_f32_e32 v164, v164
	v_rcp_f32_e32 v165, v165
	v_pk_mul_f32 v[166:167], v[110:111], v[224:225]
	v_pk_mul_f32 v[168:169], v[112:113], v[224:225]
	v_pk_mul_f32 v[170:171], v[106:107], v[224:225]
	v_pk_mul_f32 v[172:173], v[108:109], v[224:225]
	v_pk_mul_f32 v[174:175], v[102:103], v[224:225]
	v_pk_mul_f32 v[176:177], v[104:105], v[224:225]
	v_pk_mul_f32 v[178:179], v[98:99], v[224:225]
	v_pk_mul_f32 v[180:181], v[100:101], v[224:225]
	v_exp_f32_e32 v166, v166
	v_exp_f32_e32 v167, v167
	v_exp_f32_e32 v168, v168
	v_exp_f32_e32 v169, v169
	v_exp_f32_e32 v170, v170
	v_exp_f32_e32 v171, v171
	v_exp_f32_e32 v172, v172
	v_exp_f32_e32 v173, v173
	v_exp_f32_e32 v174, v174
	v_exp_f32_e32 v175, v175
	v_exp_f32_e32 v176, v176
	v_exp_f32_e32 v177, v177
	v_exp_f32_e32 v178, v178
	v_exp_f32_e32 v179, v179
	v_exp_f32_e32 v180, v180
	v_exp_f32_e32 v181, v181
	v_pk_add_f32 v[166:167], v[166:167], v[226:227]
	v_pk_add_f32 v[168:169], v[168:169], v[226:227]
	v_pk_add_f32 v[170:171], v[170:171], v[226:227]
	v_pk_add_f32 v[172:173], v[172:173], v[226:227]
	v_pk_add_f32 v[174:175], v[174:175], v[226:227]
	v_pk_add_f32 v[176:177], v[176:177], v[226:227]
	v_pk_add_f32 v[178:179], v[178:179], v[226:227]
	v_pk_add_f32 v[180:181], v[180:181], v[226:227]
	v_rcp_f32_e32 v166, v166
	v_rcp_f32_e32 v167, v167
	v_rcp_f32_e32 v168, v168
	v_rcp_f32_e32 v169, v169
	v_rcp_f32_e32 v170, v170
	v_rcp_f32_e32 v171, v171
	v_rcp_f32_e32 v172, v172
	v_rcp_f32_e32 v173, v173
	v_rcp_f32_e32 v174, v174
	v_rcp_f32_e32 v175, v175
	v_rcp_f32_e32 v176, v176
	v_rcp_f32_e32 v177, v177
	v_rcp_f32_e32 v178, v178
	v_rcp_f32_e32 v179, v179
	v_rcp_f32_e32 v180, v180
	v_rcp_f32_e32 v181, v181
	v_pk_mul_f32 v[182:183], v[94:95], v[224:225]
	v_pk_mul_f32 v[184:185], v[96:97], v[224:225]
	v_pk_mul_f32 v[186:187], v[90:91], v[224:225]
	v_pk_mul_f32 v[188:189], v[92:93], v[224:225]
	v_pk_mul_f32 v[190:191], v[86:87], v[224:225]
	v_pk_mul_f32 v[192:193], v[88:89], v[224:225]
	v_pk_mul_f32 v[194:195], v[82:83], v[224:225]
	v_pk_mul_f32 v[196:197], v[84:85], v[224:225]
	v_exp_f32_e32 v182, v182
	v_exp_f32_e32 v183, v183
	v_exp_f32_e32 v184, v184
	v_exp_f32_e32 v185, v185
	v_exp_f32_e32 v186, v186
	v_exp_f32_e32 v187, v187
	v_exp_f32_e32 v188, v188
	v_exp_f32_e32 v189, v189
	v_exp_f32_e32 v190, v190
	v_exp_f32_e32 v191, v191
	v_exp_f32_e32 v192, v192
	v_exp_f32_e32 v193, v193
	v_exp_f32_e32 v194, v194
	v_exp_f32_e32 v195, v195
	v_exp_f32_e32 v196, v196
	v_exp_f32_e32 v197, v197
	v_pk_add_f32 v[182:183], v[182:183], v[226:227]
	v_pk_add_f32 v[184:185], v[184:185], v[226:227]
	v_pk_add_f32 v[186:187], v[186:187], v[226:227]
	v_pk_add_f32 v[188:189], v[188:189], v[226:227]
	v_pk_add_f32 v[190:191], v[190:191], v[226:227]
	v_pk_add_f32 v[192:193], v[192:193], v[226:227]
	v_pk_add_f32 v[194:195], v[194:195], v[226:227]
	v_pk_add_f32 v[196:197], v[196:197], v[226:227]
	v_rcp_f32_e32 v182, v182
	v_rcp_f32_e32 v183, v183
	v_rcp_f32_e32 v184, v184
	v_rcp_f32_e32 v185, v185
	v_rcp_f32_e32 v186, v186
	v_rcp_f32_e32 v187, v187
	v_rcp_f32_e32 v188, v188
	v_rcp_f32_e32 v189, v189
	v_rcp_f32_e32 v190, v190
	v_rcp_f32_e32 v191, v191
	v_rcp_f32_e32 v192, v192
	v_rcp_f32_e32 v193, v193
	v_rcp_f32_e32 v194, v194
	v_rcp_f32_e32 v195, v195
	v_rcp_f32_e32 v196, v196
	v_rcp_f32_e32 v197, v197
	s_waitcnt vmcnt(3)
	s_barrier
	v_add_u32_e32 v253, 0x40000, v143
	s_add_i32 m0, s27, 0xe000
	s_nop 0
	global_load_lds_dwordx4 v253, s[6:7]
	ds_read_b64 v[140:141], v252 offset:0
	ds_read_b64 v[144:145], v252 offset:4096
	v_pk_mul_f32 v[230:231], v[78:79], v[224:225]
	v_pk_mul_f32 v[232:233], v[80:81], v[224:225]
	v_pk_mul_f32 v[234:235], v[74:75], v[224:225]
	v_pk_mul_f32 v[236:237], v[76:77], v[224:225]
	v_exp_f32_e32 v230, v230
	v_exp_f32_e32 v231, v231
	v_exp_f32_e32 v232, v232
	v_exp_f32_e32 v233, v233
	v_exp_f32_e32 v234, v234
	v_exp_f32_e32 v235, v235
	v_exp_f32_e32 v236, v236
	v_exp_f32_e32 v237, v237
	v_pk_add_f32 v[230:231], v[230:231], v[226:227]
	v_pk_add_f32 v[232:233], v[232:233], v[226:227]
	v_pk_add_f32 v[234:235], v[234:235], v[226:227]
	v_pk_add_f32 v[236:237], v[236:237], v[226:227]
	v_rcp_f32_e32 v230, v230
	v_rcp_f32_e32 v231, v231
	v_rcp_f32_e32 v232, v232
	v_rcp_f32_e32 v233, v233
	v_rcp_f32_e32 v234, v234
	v_rcp_f32_e32 v235, v235
	v_rcp_f32_e32 v236, v236
	v_rcp_f32_e32 v237, v237
	s_waitcnt lgkmcnt(0)
	v_lshlrev_b32_e32 v126, 16, v140
	v_and_b32_e32 v127, 0xffff0000, v140
	v_lshlrev_b32_e32 v128, 16, v141
	v_and_b32_e32 v129, 0xffff0000, v141
	v_lshlrev_b32_e32 v122, 16, v144
	v_and_b32_e32 v123, 0xffff0000, v144
	v_lshlrev_b32_e32 v124, 16, v145
	v_and_b32_e32 v125, 0xffff0000, v145
	v_pk_mul_f32 v[150:151], v[150:151], v[126:127]
	v_pk_mul_f32 v[152:153], v[152:153], v[128:129]
	v_pk_mul_f32 v[154:155], v[154:155], v[122:123]
	v_pk_mul_f32 v[156:157], v[156:157], v[124:125]
	v_pk_add_f32 v[246:247], v[150:151], v[228:229]
	v_pk_add_f32 v[248:249], v[152:153], v[228:229]
	v_pk_add_f32 v[246:247], v[246:247], v[154:155]
	v_pk_add_f32 v[248:249], v[248:249], v[156:157]
	s_waitcnt vmcnt(3)
	s_barrier
	v_add_u32_e32 v253, 0x41000, v143
	s_add_i32 m0, s27, 0x20000
	s_nop 0
	global_load_lds_dwordx4 v253, s[6:7]
	ds_read_b64 v[140:141], v252 offset:8192
	ds_read_b64 v[144:145], v252 offset:12288
	v_pk_mul_f32 v[238:239], v[70:71], v[224:225]
	v_pk_mul_f32 v[240:241], v[72:73], v[224:225]
	v_pk_mul_f32 v[242:243], v[66:67], v[224:225]
	v_pk_mul_f32 v[244:245], v[68:69], v[224:225]
	v_exp_f32_e32 v238, v238
	v_exp_f32_e32 v239, v239
	v_exp_f32_e32 v240, v240
	v_exp_f32_e32 v241, v241
	v_exp_f32_e32 v242, v242
	v_exp_f32_e32 v243, v243
	v_exp_f32_e32 v244, v244
	v_exp_f32_e32 v245, v245
	v_pk_add_f32 v[238:239], v[238:239], v[226:227]
	v_pk_add_f32 v[240:241], v[240:241], v[226:227]
	v_pk_add_f32 v[242:243], v[242:243], v[226:227]
	v_pk_add_f32 v[244:245], v[244:245], v[226:227]
	v_rcp_f32_e32 v238, v238
	v_rcp_f32_e32 v239, v239
	v_rcp_f32_e32 v240, v240
	v_rcp_f32_e32 v241, v241
	v_rcp_f32_e32 v242, v242
	v_rcp_f32_e32 v243, v243
	v_rcp_f32_e32 v244, v244
	v_rcp_f32_e32 v245, v245
	s_waitcnt lgkmcnt(0)
	v_lshlrev_b32_e32 v118, 16, v140
	v_and_b32_e32 v119, 0xffff0000, v140
	v_lshlrev_b32_e32 v120, 16, v141
	v_and_b32_e32 v121, 0xffff0000, v141
	v_lshlrev_b32_e32 v114, 16, v144
	v_and_b32_e32 v115, 0xffff0000, v144
	v_lshlrev_b32_e32 v116, 16, v145
	v_and_b32_e32 v117, 0xffff0000, v145
	v_pk_mul_f32 v[158:159], v[158:159], v[118:119]
	v_pk_mul_f32 v[160:161], v[160:161], v[120:121]
	v_pk_mul_f32 v[162:163], v[162:163], v[114:115]
	v_pk_mul_f32 v[164:165], v[164:165], v[116:117]
	v_pk_add_f32 v[246:247], v[246:247], v[158:159]
	v_pk_add_f32 v[248:249], v[248:249], v[160:161]
	v_pk_add_f32 v[246:247], v[246:247], v[162:163]
	v_pk_add_f32 v[248:249], v[248:249], v[164:165]
	v_add_u32_e32 v254, 0, v250
	v_cvt_pk_bf16_f32 v246, v246, v247
	v_cvt_pk_bf16_f32 v247, v248, v249
	v_lshl_add_u32 v254, v254, 11, v251
	s_nop 0
	global_store_dwordx2 v254, v[246:247], s[8:9]
	s_waitcnt vmcnt(4)
	s_barrier
	v_add_u32_e32 v253, 0x60000, v143
	s_add_i32 m0, s27, 0x22000
	s_nop 0
	global_load_lds_dwordx4 v253, s[6:7]
	ds_read_b64 v[140:141], v252 offset:16384
	ds_read_b64 v[144:145], v252 offset:20480
	v_pk_mul_f32 v[150:151], v[62:63], v[224:225]
	v_pk_mul_f32 v[152:153], v[64:65], v[224:225]
	v_pk_mul_f32 v[154:155], v[58:59], v[224:225]
	v_pk_mul_f32 v[156:157], v[60:61], v[224:225]
	v_exp_f32_e32 v150, v150
	v_exp_f32_e32 v151, v151
	v_exp_f32_e32 v152, v152
	v_exp_f32_e32 v153, v153
	v_exp_f32_e32 v154, v154
	v_exp_f32_e32 v155, v155
	v_exp_f32_e32 v156, v156
	v_exp_f32_e32 v157, v157
	v_pk_add_f32 v[150:151], v[150:151], v[226:227]
	v_pk_add_f32 v[152:153], v[152:153], v[226:227]
	v_pk_add_f32 v[154:155], v[154:155], v[226:227]
	v_pk_add_f32 v[156:157], v[156:157], v[226:227]
	v_rcp_f32_e32 v150, v150
	v_rcp_f32_e32 v151, v151
	v_rcp_f32_e32 v152, v152
	v_rcp_f32_e32 v153, v153
	v_rcp_f32_e32 v154, v154
	v_rcp_f32_e32 v155, v155
	v_rcp_f32_e32 v156, v156
	v_rcp_f32_e32 v157, v157
	s_waitcnt lgkmcnt(0)
	v_lshlrev_b32_e32 v110, 16, v140
	v_and_b32_e32 v111, 0xffff0000, v140
	v_lshlrev_b32_e32 v112, 16, v141
	v_and_b32_e32 v113, 0xffff0000, v141
	v_lshlrev_b32_e32 v106, 16, v144
	v_and_b32_e32 v107, 0xffff0000, v144
	v_lshlrev_b32_e32 v108, 16, v145
	v_and_b32_e32 v109, 0xffff0000, v145
	v_pk_mul_f32 v[166:167], v[166:167], v[110:111]
	v_pk_mul_f32 v[168:169], v[168:169], v[112:113]
	v_pk_mul_f32 v[170:171], v[170:171], v[106:107]
	v_pk_mul_f32 v[172:173], v[172:173], v[108:109]
	v_pk_add_f32 v[246:247], v[166:167], v[228:229]
	v_pk_add_f32 v[248:249], v[168:169], v[228:229]
	v_pk_add_f32 v[246:247], v[246:247], v[170:171]
	v_pk_add_f32 v[248:249], v[248:249], v[172:173]
	s_waitcnt vmcnt(4)
	s_barrier
	v_add_u32_e32 v253, 0x61000, v143
	s_add_i32 m0, s27, 0x24000
	s_nop 0
	global_load_lds_dwordx4 v253, s[6:7]
	ds_read_b64 v[140:141], v198 offset:0
	ds_read_b64 v[144:145], v198 offset:4096
	v_pk_mul_f32 v[158:159], v[54:55], v[224:225]
	v_pk_mul_f32 v[160:161], v[56:57], v[224:225]
	v_pk_mul_f32 v[162:163], v[50:51], v[224:225]
	v_pk_mul_f32 v[164:165], v[52:53], v[224:225]
	v_exp_f32_e32 v158, v158
	v_exp_f32_e32 v159, v159
	v_exp_f32_e32 v160, v160
	v_exp_f32_e32 v161, v161
	v_exp_f32_e32 v162, v162
	v_exp_f32_e32 v163, v163
	v_exp_f32_e32 v164, v164
	v_exp_f32_e32 v165, v165
	v_pk_add_f32 v[158:159], v[158:159], v[226:227]
	v_pk_add_f32 v[160:161], v[160:161], v[226:227]
	v_pk_add_f32 v[162:163], v[162:163], v[226:227]
	v_pk_add_f32 v[164:165], v[164:165], v[226:227]
	v_rcp_f32_e32 v158, v158
	v_rcp_f32_e32 v159, v159
	v_rcp_f32_e32 v160, v160
	v_rcp_f32_e32 v161, v161
	v_rcp_f32_e32 v162, v162
	v_rcp_f32_e32 v163, v163
	v_rcp_f32_e32 v164, v164
	v_rcp_f32_e32 v165, v165
	s_waitcnt lgkmcnt(0)
	v_lshlrev_b32_e32 v102, 16, v140
	v_and_b32_e32 v103, 0xffff0000, v140
	v_lshlrev_b32_e32 v104, 16, v141
	v_and_b32_e32 v105, 0xffff0000, v141
	v_lshlrev_b32_e32 v98, 16, v144
	v_and_b32_e32 v99, 0xffff0000, v144
	v_lshlrev_b32_e32 v100, 16, v145
	v_and_b32_e32 v101, 0xffff0000, v145
	v_pk_mul_f32 v[174:175], v[174:175], v[102:103]
	v_pk_mul_f32 v[176:177], v[176:177], v[104:105]
	v_pk_mul_f32 v[178:179], v[178:179], v[98:99]
	v_pk_mul_f32 v[180:181], v[180:181], v[100:101]
	v_pk_add_f32 v[246:247], v[246:247], v[174:175]
	v_pk_add_f32 v[248:249], v[248:249], v[176:177]
	v_pk_add_f32 v[246:247], v[246:247], v[178:179]
	v_pk_add_f32 v[248:249], v[248:249], v[180:181]
	v_add_u32_e32 v254, 16, v250
	v_cvt_pk_bf16_f32 v246, v246, v247
	v_cvt_pk_bf16_f32 v247, v248, v249
	v_lshl_add_u32 v254, v254, 11, v251
	s_nop 0
	global_store_dwordx2 v254, v[246:247], s[8:9]
	s_waitcnt vmcnt(5)
	s_barrier
	v_add_u32_e32 v253, 0x100000, v143
	s_add_i32 m0, s27, 0xc000
	s_nop 0
	global_load_lds_dwordx4 v253, s[6:7]
	ds_read_b64 v[140:141], v198 offset:8192
	ds_read_b64 v[144:145], v198 offset:12288
	v_pk_mul_f32 v[166:167], v[46:47], v[224:225]
	v_pk_mul_f32 v[168:169], v[48:49], v[224:225]
	v_pk_mul_f32 v[170:171], v[42:43], v[224:225]
	v_pk_mul_f32 v[172:173], v[44:45], v[224:225]
	v_exp_f32_e32 v166, v166
	v_exp_f32_e32 v167, v167
	v_exp_f32_e32 v168, v168
	v_exp_f32_e32 v169, v169
	v_exp_f32_e32 v170, v170
	v_exp_f32_e32 v171, v171
	v_exp_f32_e32 v172, v172
	v_exp_f32_e32 v173, v173
	v_pk_add_f32 v[166:167], v[166:167], v[226:227]
	v_pk_add_f32 v[168:169], v[168:169], v[226:227]
	v_pk_add_f32 v[170:171], v[170:171], v[226:227]
	v_pk_add_f32 v[172:173], v[172:173], v[226:227]
	v_rcp_f32_e32 v166, v166
	v_rcp_f32_e32 v167, v167
	v_rcp_f32_e32 v168, v168
	v_rcp_f32_e32 v169, v169
	v_rcp_f32_e32 v170, v170
	v_rcp_f32_e32 v171, v171
	v_rcp_f32_e32 v172, v172
	v_rcp_f32_e32 v173, v173
	s_waitcnt lgkmcnt(0)
	v_lshlrev_b32_e32 v94, 16, v140
	v_and_b32_e32 v95, 0xffff0000, v140
	v_lshlrev_b32_e32 v96, 16, v141
	v_and_b32_e32 v97, 0xffff0000, v141
	v_lshlrev_b32_e32 v90, 16, v144
	v_and_b32_e32 v91, 0xffff0000, v144
	v_lshlrev_b32_e32 v92, 16, v145
	v_and_b32_e32 v93, 0xffff0000, v145
	v_pk_mul_f32 v[182:183], v[182:183], v[94:95]
	v_pk_mul_f32 v[184:185], v[184:185], v[96:97]
	v_pk_mul_f32 v[186:187], v[186:187], v[90:91]
	v_pk_mul_f32 v[188:189], v[188:189], v[92:93]
	v_pk_add_f32 v[246:247], v[182:183], v[228:229]
	v_pk_add_f32 v[248:249], v[184:185], v[228:229]
	v_pk_add_f32 v[246:247], v[246:247], v[186:187]
	v_pk_add_f32 v[248:249], v[248:249], v[188:189]
	s_waitcnt vmcnt(5)
	s_barrier
	v_add_u32_e32 v253, 0x101000, v143
	s_add_i32 m0, s27, 0xe000
	s_nop 0
	global_load_lds_dwordx4 v253, s[6:7]
	ds_read_b64 v[140:141], v252 offset:0
	ds_read_b64 v[144:145], v252 offset:4096
	v_pk_mul_f32 v[174:175], v[38:39], v[224:225]
	v_pk_mul_f32 v[176:177], v[40:41], v[224:225]
	v_pk_mul_f32 v[178:179], v[34:35], v[224:225]
	v_pk_mul_f32 v[180:181], v[36:37], v[224:225]
	v_exp_f32_e32 v174, v174
	v_exp_f32_e32 v175, v175
	v_exp_f32_e32 v176, v176
	v_exp_f32_e32 v177, v177
	v_exp_f32_e32 v178, v178
	v_exp_f32_e32 v179, v179
	v_exp_f32_e32 v180, v180
	v_exp_f32_e32 v181, v181
	v_pk_add_f32 v[174:175], v[174:175], v[226:227]
	v_pk_add_f32 v[176:177], v[176:177], v[226:227]
	v_pk_add_f32 v[178:179], v[178:179], v[226:227]
	v_pk_add_f32 v[180:181], v[180:181], v[226:227]
	v_rcp_f32_e32 v174, v174
	v_rcp_f32_e32 v175, v175
	v_rcp_f32_e32 v176, v176
	v_rcp_f32_e32 v177, v177
	v_rcp_f32_e32 v178, v178
	v_rcp_f32_e32 v179, v179
	v_rcp_f32_e32 v180, v180
	v_rcp_f32_e32 v181, v181
	s_waitcnt lgkmcnt(0)
	v_lshlrev_b32_e32 v86, 16, v140
	v_and_b32_e32 v87, 0xffff0000, v140
	v_lshlrev_b32_e32 v88, 16, v141
	v_and_b32_e32 v89, 0xffff0000, v141
	v_lshlrev_b32_e32 v82, 16, v144
	v_and_b32_e32 v83, 0xffff0000, v144
	v_lshlrev_b32_e32 v84, 16, v145
	v_and_b32_e32 v85, 0xffff0000, v145
	v_pk_mul_f32 v[190:191], v[190:191], v[86:87]
	v_pk_mul_f32 v[192:193], v[192:193], v[88:89]
	v_pk_mul_f32 v[194:195], v[194:195], v[82:83]
	v_pk_mul_f32 v[196:197], v[196:197], v[84:85]
	v_pk_add_f32 v[246:247], v[246:247], v[190:191]
	v_pk_add_f32 v[248:249], v[248:249], v[192:193]
	v_pk_add_f32 v[246:247], v[246:247], v[194:195]
	v_pk_add_f32 v[248:249], v[248:249], v[196:197]
	v_add_u32_e32 v254, 32, v250
	v_cvt_pk_bf16_f32 v246, v246, v247
	v_cvt_pk_bf16_f32 v247, v248, v249
	v_lshl_add_u32 v254, v254, 11, v251
	s_nop 0
	global_store_dwordx2 v254, v[246:247], s[8:9]
	s_waitcnt vmcnt(5)
	s_barrier
	v_add_u32_e32 v253, 0x120000, v143
	s_add_i32 m0, s27, 0x20000
	s_nop 0
	global_load_lds_dwordx4 v253, s[6:7]
	ds_read_b64 v[140:141], v252 offset:8192
	ds_read_b64 v[144:145], v252 offset:12288
	v_pk_mul_f32 v[182:183], v[30:31], v[224:225]
	v_pk_mul_f32 v[184:185], v[32:33], v[224:225]
	v_pk_mul_f32 v[186:187], v[26:27], v[224:225]
	v_pk_mul_f32 v[188:189], v[28:29], v[224:225]
	v_exp_f32_e32 v182, v182
	v_exp_f32_e32 v183, v183
	v_exp_f32_e32 v184, v184
	v_exp_f32_e32 v185, v185
	v_exp_f32_e32 v186, v186
	v_exp_f32_e32 v187, v187
	v_exp_f32_e32 v188, v188
	v_exp_f32_e32 v189, v189
	v_pk_add_f32 v[182:183], v[182:183], v[226:227]
	v_pk_add_f32 v[184:185], v[184:185], v[226:227]
	v_pk_add_f32 v[186:187], v[186:187], v[226:227]
	v_pk_add_f32 v[188:189], v[188:189], v[226:227]
	v_rcp_f32_e32 v182, v182
	v_rcp_f32_e32 v183, v183
	v_rcp_f32_e32 v184, v184
	v_rcp_f32_e32 v185, v185
	v_rcp_f32_e32 v186, v186
	v_rcp_f32_e32 v187, v187
	v_rcp_f32_e32 v188, v188
	v_rcp_f32_e32 v189, v189
	s_waitcnt lgkmcnt(0)
	v_lshlrev_b32_e32 v78, 16, v140
	v_and_b32_e32 v79, 0xffff0000, v140
	v_lshlrev_b32_e32 v80, 16, v141
	v_and_b32_e32 v81, 0xffff0000, v141
	v_lshlrev_b32_e32 v74, 16, v144
	v_and_b32_e32 v75, 0xffff0000, v144
	v_lshlrev_b32_e32 v76, 16, v145
	v_and_b32_e32 v77, 0xffff0000, v145
	v_pk_mul_f32 v[230:231], v[230:231], v[78:79]
	v_pk_mul_f32 v[232:233], v[232:233], v[80:81]
	v_pk_mul_f32 v[234:235], v[234:235], v[74:75]
	v_pk_mul_f32 v[236:237], v[236:237], v[76:77]
	v_pk_add_f32 v[246:247], v[230:231], v[228:229]
	v_pk_add_f32 v[248:249], v[232:233], v[228:229]
	v_pk_add_f32 v[246:247], v[246:247], v[234:235]
	v_pk_add_f32 v[248:249], v[248:249], v[236:237]
	s_waitcnt vmcnt(5)
	s_barrier
	v_add_u32_e32 v253, 0x121000, v143
	s_add_i32 m0, s27, 0x22000
	s_nop 0
	global_load_lds_dwordx4 v253, s[6:7]
	ds_read_b64 v[140:141], v252 offset:16384
	ds_read_b64 v[144:145], v252 offset:20480
	v_pk_mul_f32 v[190:191], v[22:23], v[224:225]
	v_pk_mul_f32 v[192:193], v[24:25], v[224:225]
	v_pk_mul_f32 v[194:195], v[18:19], v[224:225]
	v_pk_mul_f32 v[196:197], v[20:21], v[224:225]
	v_exp_f32_e32 v190, v190
	v_exp_f32_e32 v191, v191
	v_exp_f32_e32 v192, v192
	v_exp_f32_e32 v193, v193
	v_exp_f32_e32 v194, v194
	v_exp_f32_e32 v195, v195
	v_exp_f32_e32 v196, v196
	v_exp_f32_e32 v197, v197
	v_pk_add_f32 v[190:191], v[190:191], v[226:227]
	v_pk_add_f32 v[192:193], v[192:193], v[226:227]
	v_pk_add_f32 v[194:195], v[194:195], v[226:227]
	v_pk_add_f32 v[196:197], v[196:197], v[226:227]
	v_rcp_f32_e32 v190, v190
	v_rcp_f32_e32 v191, v191
	v_rcp_f32_e32 v192, v192
	v_rcp_f32_e32 v193, v193
	v_rcp_f32_e32 v194, v194
	v_rcp_f32_e32 v195, v195
	v_rcp_f32_e32 v196, v196
	v_rcp_f32_e32 v197, v197
	s_waitcnt lgkmcnt(0)
	v_lshlrev_b32_e32 v70, 16, v140
	v_and_b32_e32 v71, 0xffff0000, v140
	v_lshlrev_b32_e32 v72, 16, v141
	v_and_b32_e32 v73, 0xffff0000, v141
	v_lshlrev_b32_e32 v66, 16, v144
	v_and_b32_e32 v67, 0xffff0000, v144
	v_lshlrev_b32_e32 v68, 16, v145
	v_and_b32_e32 v69, 0xffff0000, v145
	v_pk_mul_f32 v[238:239], v[238:239], v[70:71]
	v_pk_mul_f32 v[240:241], v[240:241], v[72:73]
	v_pk_mul_f32 v[242:243], v[242:243], v[66:67]
	v_pk_mul_f32 v[244:245], v[244:245], v[68:69]
	v_pk_add_f32 v[246:247], v[246:247], v[238:239]
	v_pk_add_f32 v[248:249], v[248:249], v[240:241]
	v_pk_add_f32 v[246:247], v[246:247], v[242:243]
	v_pk_add_f32 v[248:249], v[248:249], v[244:245]
	v_add_u32_e32 v254, 48, v250
	v_cvt_pk_bf16_f32 v246, v246, v247
	v_cvt_pk_bf16_f32 v247, v248, v249
	v_lshl_add_u32 v254, v254, 11, v251
	s_nop 0
	global_store_dwordx2 v254, v[246:247], s[8:9]
	s_waitcnt vmcnt(5)
	s_barrier
	v_add_u32_e32 v253, 0x140000, v143
	s_add_i32 m0, s27, 0x24000
	s_nop 0
	global_load_lds_dwordx4 v253, s[6:7]
	ds_read_b64 v[140:141], v198 offset:0
	ds_read_b64 v[144:145], v198 offset:4096
	v_pk_mul_f32 v[230:231], v[14:15], v[224:225]
	v_pk_mul_f32 v[232:233], v[16:17], v[224:225]
	v_pk_mul_f32 v[234:235], v[10:11], v[224:225]
	v_pk_mul_f32 v[236:237], v[12:13], v[224:225]
	v_exp_f32_e32 v230, v230
	v_exp_f32_e32 v231, v231
	v_exp_f32_e32 v232, v232
	v_exp_f32_e32 v233, v233
	v_exp_f32_e32 v234, v234
	v_exp_f32_e32 v235, v235
	v_exp_f32_e32 v236, v236
	v_exp_f32_e32 v237, v237
	v_pk_add_f32 v[230:231], v[230:231], v[226:227]
	v_pk_add_f32 v[232:233], v[232:233], v[226:227]
	v_pk_add_f32 v[234:235], v[234:235], v[226:227]
	v_pk_add_f32 v[236:237], v[236:237], v[226:227]
	v_rcp_f32_e32 v230, v230
	v_rcp_f32_e32 v231, v231
	v_rcp_f32_e32 v232, v232
	v_rcp_f32_e32 v233, v233
	v_rcp_f32_e32 v234, v234
	v_rcp_f32_e32 v235, v235
	v_rcp_f32_e32 v236, v236
	v_rcp_f32_e32 v237, v237
	s_waitcnt lgkmcnt(0)
	v_lshlrev_b32_e32 v62, 16, v140
	v_and_b32_e32 v63, 0xffff0000, v140
	v_lshlrev_b32_e32 v64, 16, v141
	v_and_b32_e32 v65, 0xffff0000, v141
	v_lshlrev_b32_e32 v58, 16, v144
	v_and_b32_e32 v59, 0xffff0000, v144
	v_lshlrev_b32_e32 v60, 16, v145
	v_and_b32_e32 v61, 0xffff0000, v145
	v_pk_mul_f32 v[150:151], v[150:151], v[62:63]
	v_pk_mul_f32 v[152:153], v[152:153], v[64:65]
	v_pk_mul_f32 v[154:155], v[154:155], v[58:59]
	v_pk_mul_f32 v[156:157], v[156:157], v[60:61]
	v_pk_add_f32 v[246:247], v[150:151], v[228:229]
	v_pk_add_f32 v[248:249], v[152:153], v[228:229]
	v_pk_add_f32 v[246:247], v[246:247], v[154:155]
	v_pk_add_f32 v[248:249], v[248:249], v[156:157]
	s_waitcnt vmcnt(5)
	s_barrier
	v_add_u32_e32 v253, 0x141000, v143
	s_add_i32 m0, s27, 0xc000
	s_nop 0
	global_load_lds_dwordx4 v253, s[6:7]
	ds_read_b64 v[140:141], v198 offset:8192
	ds_read_b64 v[144:145], v198 offset:12288
	v_pk_mul_f32 v[238:239], v[6:7], v[224:225]
	v_pk_mul_f32 v[240:241], v[8:9], v[224:225]
	v_pk_mul_f32 v[242:243], v[2:3], v[224:225]
	v_pk_mul_f32 v[244:245], v[4:5], v[224:225]
	v_exp_f32_e32 v238, v238
	v_exp_f32_e32 v239, v239
	v_exp_f32_e32 v240, v240
	v_exp_f32_e32 v241, v241
	v_exp_f32_e32 v242, v242
	v_exp_f32_e32 v243, v243
	v_exp_f32_e32 v244, v244
	v_exp_f32_e32 v245, v245
	v_pk_add_f32 v[238:239], v[238:239], v[226:227]
	v_pk_add_f32 v[240:241], v[240:241], v[226:227]
	v_pk_add_f32 v[242:243], v[242:243], v[226:227]
	v_pk_add_f32 v[244:245], v[244:245], v[226:227]
	v_rcp_f32_e32 v238, v238
	v_rcp_f32_e32 v239, v239
	v_rcp_f32_e32 v240, v240
	v_rcp_f32_e32 v241, v241
	v_rcp_f32_e32 v242, v242
	v_rcp_f32_e32 v243, v243
	v_rcp_f32_e32 v244, v244
	v_rcp_f32_e32 v245, v245
	s_waitcnt lgkmcnt(0)
	v_lshlrev_b32_e32 v54, 16, v140
	v_and_b32_e32 v55, 0xffff0000, v140
	v_lshlrev_b32_e32 v56, 16, v141
	v_and_b32_e32 v57, 0xffff0000, v141
	v_lshlrev_b32_e32 v50, 16, v144
	v_and_b32_e32 v51, 0xffff0000, v144
	v_lshlrev_b32_e32 v52, 16, v145
	v_and_b32_e32 v53, 0xffff0000, v145
	v_pk_mul_f32 v[158:159], v[158:159], v[54:55]
	v_pk_mul_f32 v[160:161], v[160:161], v[56:57]
	v_pk_mul_f32 v[162:163], v[162:163], v[50:51]
	v_pk_mul_f32 v[164:165], v[164:165], v[52:53]
	v_pk_add_f32 v[246:247], v[246:247], v[158:159]
	v_pk_add_f32 v[248:249], v[248:249], v[160:161]
	v_pk_add_f32 v[246:247], v[246:247], v[162:163]
	v_pk_add_f32 v[248:249], v[248:249], v[164:165]
	v_add_u32_e32 v254, 128, v250
	v_cvt_pk_bf16_f32 v246, v246, v247
	v_cvt_pk_bf16_f32 v247, v248, v249
	v_lshl_add_u32 v254, v254, 11, v251
	s_nop 0
	global_store_dwordx2 v254, v[246:247], s[8:9]
	s_waitcnt vmcnt(5)
	s_barrier
	v_add_u32_e32 v253, 0x160000, v143
	s_add_i32 m0, s27, 0xe000
	s_nop 0
	global_load_lds_dwordx4 v253, s[6:7]
	ds_read_b64 v[140:141], v252 offset:0
	ds_read_b64 v[144:145], v252 offset:4096
	s_waitcnt lgkmcnt(0)
	v_lshlrev_b32_e32 v46, 16, v140
	v_and_b32_e32 v47, 0xffff0000, v140
	v_lshlrev_b32_e32 v48, 16, v141
	v_and_b32_e32 v49, 0xffff0000, v141
	v_lshlrev_b32_e32 v42, 16, v144
	v_and_b32_e32 v43, 0xffff0000, v144
	v_lshlrev_b32_e32 v44, 16, v145
	v_and_b32_e32 v45, 0xffff0000, v145
	v_pk_mul_f32 v[166:167], v[166:167], v[46:47]
	v_pk_mul_f32 v[168:169], v[168:169], v[48:49]
	v_pk_mul_f32 v[170:171], v[170:171], v[42:43]
	v_pk_mul_f32 v[172:173], v[172:173], v[44:45]
	v_pk_add_f32 v[246:247], v[166:167], v[228:229]
	v_pk_add_f32 v[248:249], v[168:169], v[228:229]
	v_pk_add_f32 v[246:247], v[246:247], v[170:171]
	v_pk_add_f32 v[248:249], v[248:249], v[172:173]
	s_waitcnt vmcnt(5)
	s_barrier
	v_add_u32_e32 v253, 0x161000, v143
	s_add_i32 m0, s27, 0x20000
	s_nop 0
	global_load_lds_dwordx4 v253, s[6:7]
	ds_read_b64 v[140:141], v252 offset:8192
	ds_read_b64 v[144:145], v252 offset:12288
	s_waitcnt lgkmcnt(0)
	v_lshlrev_b32_e32 v38, 16, v140
	v_and_b32_e32 v39, 0xffff0000, v140
	v_lshlrev_b32_e32 v40, 16, v141
	v_and_b32_e32 v41, 0xffff0000, v141
	v_lshlrev_b32_e32 v34, 16, v144
	v_and_b32_e32 v35, 0xffff0000, v144
	v_lshlrev_b32_e32 v36, 16, v145
	v_and_b32_e32 v37, 0xffff0000, v145
	v_pk_mul_f32 v[174:175], v[174:175], v[38:39]
	v_pk_mul_f32 v[176:177], v[176:177], v[40:41]
	v_pk_mul_f32 v[178:179], v[178:179], v[34:35]
	v_pk_mul_f32 v[180:181], v[180:181], v[36:37]
	v_pk_add_f32 v[246:247], v[246:247], v[174:175]
	v_pk_add_f32 v[248:249], v[248:249], v[176:177]
	v_pk_add_f32 v[246:247], v[246:247], v[178:179]
	v_pk_add_f32 v[248:249], v[248:249], v[180:181]
	v_add_u32_e32 v254, 144, v250
	v_cvt_pk_bf16_f32 v246, v246, v247
	v_cvt_pk_bf16_f32 v247, v248, v249
	v_lshl_add_u32 v254, v254, 11, v251
	s_nop 0
	global_store_dwordx2 v254, v[246:247], s[8:9]
	s_waitcnt vmcnt(5)
	s_barrier
	ds_read_b64 v[140:141], v252 offset:16384
	ds_read_b64 v[144:145], v252 offset:20480
	s_waitcnt lgkmcnt(0)
	v_lshlrev_b32_e32 v30, 16, v140
	v_and_b32_e32 v31, 0xffff0000, v140
	v_lshlrev_b32_e32 v32, 16, v141
	v_and_b32_e32 v33, 0xffff0000, v141
	v_lshlrev_b32_e32 v26, 16, v144
	v_and_b32_e32 v27, 0xffff0000, v144
	v_lshlrev_b32_e32 v28, 16, v145
	v_and_b32_e32 v29, 0xffff0000, v145
	v_pk_mul_f32 v[182:183], v[182:183], v[30:31]
	v_pk_mul_f32 v[184:185], v[184:185], v[32:33]
	v_pk_mul_f32 v[186:187], v[186:187], v[26:27]
	v_pk_mul_f32 v[188:189], v[188:189], v[28:29]
	v_pk_add_f32 v[246:247], v[182:183], v[228:229]
	v_pk_add_f32 v[248:249], v[184:185], v[228:229]
	v_pk_add_f32 v[246:247], v[246:247], v[186:187]
	v_pk_add_f32 v[248:249], v[248:249], v[188:189]
	s_waitcnt vmcnt(4)
	s_barrier
	ds_read_b64 v[140:141], v198 offset:0
	ds_read_b64 v[144:145], v198 offset:4096
	s_waitcnt lgkmcnt(0)
	v_lshlrev_b32_e32 v22, 16, v140
	v_and_b32_e32 v23, 0xffff0000, v140
	v_lshlrev_b32_e32 v24, 16, v141
	v_and_b32_e32 v25, 0xffff0000, v141
	v_lshlrev_b32_e32 v18, 16, v144
	v_and_b32_e32 v19, 0xffff0000, v144
	v_lshlrev_b32_e32 v20, 16, v145
	v_and_b32_e32 v21, 0xffff0000, v145
	v_pk_mul_f32 v[190:191], v[190:191], v[22:23]
	v_pk_mul_f32 v[192:193], v[192:193], v[24:25]
	v_pk_mul_f32 v[194:195], v[194:195], v[18:19]
	v_pk_mul_f32 v[196:197], v[196:197], v[20:21]
	v_pk_add_f32 v[246:247], v[246:247], v[190:191]
	v_pk_add_f32 v[248:249], v[248:249], v[192:193]
	v_pk_add_f32 v[246:247], v[246:247], v[194:195]
	v_pk_add_f32 v[248:249], v[248:249], v[196:197]
	v_add_u32_e32 v254, 160, v250
	v_cvt_pk_bf16_f32 v246, v246, v247
	v_cvt_pk_bf16_f32 v247, v248, v249
	v_lshl_add_u32 v254, v254, 11, v251
	s_nop 0
	global_store_dwordx2 v254, v[246:247], s[8:9]
	s_waitcnt vmcnt(3)
	s_barrier
	ds_read_b64 v[140:141], v198 offset:8192
	ds_read_b64 v[144:145], v198 offset:12288
	s_waitcnt lgkmcnt(0)
	v_lshlrev_b32_e32 v14, 16, v140
	v_and_b32_e32 v15, 0xffff0000, v140
	v_lshlrev_b32_e32 v16, 16, v141
	v_and_b32_e32 v17, 0xffff0000, v141
	v_lshlrev_b32_e32 v10, 16, v144
	v_and_b32_e32 v11, 0xffff0000, v144
	v_lshlrev_b32_e32 v12, 16, v145
	v_and_b32_e32 v13, 0xffff0000, v145
	v_pk_mul_f32 v[230:231], v[230:231], v[14:15]
	v_pk_mul_f32 v[232:233], v[232:233], v[16:17]
	v_pk_mul_f32 v[234:235], v[234:235], v[10:11]
	v_pk_mul_f32 v[236:237], v[236:237], v[12:13]
	v_pk_add_f32 v[246:247], v[230:231], v[228:229]
	v_pk_add_f32 v[248:249], v[232:233], v[228:229]
	v_pk_add_f32 v[246:247], v[246:247], v[234:235]
	v_pk_add_f32 v[248:249], v[248:249], v[236:237]
	s_waitcnt vmcnt(2)
	s_barrier
	ds_read_b64 v[140:141], v252 offset:0
	ds_read_b64 v[144:145], v252 offset:4096
	s_waitcnt lgkmcnt(0)
	v_lshlrev_b32_e32 v6, 16, v140
	v_and_b32_e32 v7, 0xffff0000, v140
	v_lshlrev_b32_e32 v8, 16, v141
	v_and_b32_e32 v9, 0xffff0000, v141
	v_lshlrev_b32_e32 v2, 16, v144
	v_and_b32_e32 v3, 0xffff0000, v144
	v_lshlrev_b32_e32 v4, 16, v145
	v_and_b32_e32 v5, 0xffff0000, v145
	v_pk_mul_f32 v[238:239], v[238:239], v[6:7]
	v_pk_mul_f32 v[240:241], v[240:241], v[8:9]
	v_pk_mul_f32 v[242:243], v[242:243], v[2:3]
	v_pk_mul_f32 v[244:245], v[244:245], v[4:5]
	v_pk_add_f32 v[246:247], v[246:247], v[238:239]
	v_pk_add_f32 v[248:249], v[248:249], v[240:241]
	v_pk_add_f32 v[246:247], v[246:247], v[242:243]
	v_pk_add_f32 v[248:249], v[248:249], v[244:245]
	v_add_u32_e32 v254, 176, v250
	v_cvt_pk_bf16_f32 v246, v246, v247
	v_cvt_pk_bf16_f32 v247, v248, v249
	v_lshl_add_u32 v254, v254, 11, v251
	s_nop 0
	global_store_dwordx2 v254, v[246:247], s[8:9]
	s_mov_b64 s[26:27], -1
	s_andn2_b64 vcc, exec, s[4:5]
	s_cbranch_vccnz .LBB0_1599
	s_andn2_b64 vcc, exec, s[0:1]
	s_cbranch_vccnz .LBB0_1598
	s_barrier
	s_branch .LBB0_1598
